# split retention (2 workgroups per head) + 2 producers per head + 8 producer waves + write-through publish every round
# baseline (speedup 1.0000x reference)
; DEVINL void rw_project_head(const Ctx& c, int layer, int b, int hd, int pj, int nP, unsigned* cnt, unsigned char* lds) {
;     ...
;         asm volatile("s_waitcnt vmcnt(0)" ::: "memory");
;         __syncthreads();
;         if (threadIdx.x == 0) {
;             __builtin_amdgcn_fence(__ATOMIC_RELEASE, "agent");
;             __hip_atomic_store(cnt, (unsigned)(layer * 16 + round + 1), __ATOMIC_RELAXED, __HIP_MEMORY_SCOPE_AGENT);
;         }
.LBB0_237:
	s_or_b64 exec, exec, s[12:13]
	s_waitcnt vmcnt(0)
	s_waitcnt vmcnt(63) expcnt(7) lgkmcnt(15)
	s_barrier
	s_mov_b64 s[0:1], exec
	v_cmp_eq_u32_e32 vcc, 0x1c0, v160
	s_nop 0
	s_and_b64 s[12:13], s[0:1], vcc
	s_mov_b64 exec, s[12:13]
	s_cbranch_execz .LBB0_140
	s_add_i32 s12, s16, s20
	s_cmp_lt_u32 s12, s17
	s_cbranch_scc0 .Lpub_do
	s_sub_i32 s13, s19, 1
	s_and_b32 s13, s13, 15
	s_movk_i32 s12, 0x3ff
	s_movk_i32 s14, 0x3ff
	s_cmp_eq_u32 s30, 3
	s_cselect_b32 s12, s14, s12
	s_bitcmp1_b32 s12, s13
	s_cbranch_scc0 .LBB0_140
